# plus: SwiGLU (GU) epilogue rewritten by hand: row-stat loads, cross-lane sums and rsqrt batched for the 8 row groups, silu chains grouped by four, stores not waited
# speedup vs baseline: 1.0104x; 1.0055x over previous
; __device__ __forceinline__ float row_rs4(const float* ssq, size_t row, int fq) {
;     const f32x4 a = *(const f32x4*)(ssq + row * 16 + 4 * fq);
;     float s = (a[0] + a[1]) + (a[2] + a[3]);
;     s += __shfl_xor(s, 16); s += __shfl_xor(s, 32);
;     return rsqrtf(s * (1.0f / DM) + EPSN);
;     __device__ __forceinline__ void operator()(const pg8::f32x4 (&acc)[2][2][4][2], const pg8::Unit& u, int wr, int wc, int fr, int fq) const {
;         const int row0 = u.pm * 256 + wr * 64 + fr, col0 = u.pn * 128 + wc * 32 + 8 * fq;
; #pragma unroll
;         for (int ai = 0; ai < 2; ++ai)
; #pragma unroll
;             for (int m = 0; m < 4; ++m) {
;                 const size_t row = (size_t)(row0 + ai * 128 + m * 16);
;                 const float rs = row_rs4(ssq, row, fq);
;                 const pg8::f32x4 g0 = acc[ai][0][m][0] * rs, g1 = acc[ai][0][m][1] * rs, u0 = acc[ai][1][m][0] * rs, u1 = acc[ai][1][m][1] * rs;
.LBB0_160:
	v_and_b32_e32 v147, 64, v175
	v_xor_b32_e32 v145, 16, v175
	v_add_u32_e32 v147, 64, v147
	v_cmp_lt_i32_e32 vcc, v145, v147
	v_lshl_add_u32 v144, s31, 8, v131
	s_mov_b32 s9, 0x800000
	v_cndmask_b32_e32 v145, v175, v145, vcc
	v_lshlrev_b32_e32 v151, 2, v145
	v_xor_b32_e32 v145, 32, v175
	v_cmp_lt_i32_e32 vcc, v145, v147
	v_readlane_b32 s34, v253, 38
	v_lshl_or_b32 v146, s30, 7, v149
	v_cndmask_b32_e32 v145, v175, v145, vcc
	v_lshlrev_b32_e32 v152, 2, v145
	v_readlane_b32 s35, v253, 39
	s_movk_i32 s11, 0x1600
	v_ashrrev_i32_e32 v147, 31, v146
	v_lshlrev_b64 v[154:155], 1, v[146:147]
	v_mov_b64_e32 v[156:157], s[34:35]
	v_mov_b32_e32 v232, v144
	v_ashrrev_i32_e32 v233, 31, v232
	v_lshlrev_b64 v[232:233], 6, v[232:233]
	v_lshl_add_u64 v[232:233], v[138:139], 0, v[232:233]
	global_load_dwordx4 v[200:203], v[232:233], off
	v_add_u32_e32 v232, 0x10, v144
	v_ashrrev_i32_e32 v233, 31, v232
	v_lshlrev_b64 v[232:233], 6, v[232:233]
	v_lshl_add_u64 v[232:233], v[138:139], 0, v[232:233]
	global_load_dwordx4 v[204:207], v[232:233], off
	v_add_u32_e32 v232, 0x20, v144
	v_ashrrev_i32_e32 v233, 31, v232
	v_lshlrev_b64 v[232:233], 6, v[232:233]
	v_lshl_add_u64 v[232:233], v[138:139], 0, v[232:233]
	global_load_dwordx4 v[208:211], v[232:233], off
	v_add_u32_e32 v232, 0x30, v144
	v_ashrrev_i32_e32 v233, 31, v232
	v_lshlrev_b64 v[232:233], 6, v[232:233]
	v_lshl_add_u64 v[232:233], v[138:139], 0, v[232:233]
	global_load_dwordx4 v[212:215], v[232:233], off
	v_add_u32_e32 v232, 0x80, v144
	v_ashrrev_i32_e32 v233, 31, v232
	v_lshlrev_b64 v[232:233], 6, v[232:233]
	v_lshl_add_u64 v[232:233], v[138:139], 0, v[232:233]
	global_load_dwordx4 v[216:219], v[232:233], off
	v_add_u32_e32 v232, 0x90, v144
	v_ashrrev_i32_e32 v233, 31, v232
	v_lshlrev_b64 v[232:233], 6, v[232:233]
	v_lshl_add_u64 v[232:233], v[138:139], 0, v[232:233]
	global_load_dwordx4 v[220:223], v[232:233], off
	v_add_u32_e32 v232, 0xa0, v144
	v_ashrrev_i32_e32 v233, 31, v232
	v_lshlrev_b64 v[232:233], 6, v[232:233]
	v_lshl_add_u64 v[232:233], v[138:139], 0, v[232:233]
	global_load_dwordx4 v[224:227], v[232:233], off
	v_add_u32_e32 v232, 0xb0, v144
	v_ashrrev_i32_e32 v233, 31, v232
	v_lshlrev_b64 v[232:233], 6, v[232:233]
	v_lshl_add_u64 v[232:233], v[138:139], 0, v[232:233]
	global_load_dwordx4 v[228:231], v[232:233], off
	s_waitcnt vmcnt(0)
	v_add_f32_e32 v234, v201, v200
	v_add_f32_e32 v242, v202, v203
	v_add_f32_e32 v234, v234, v242
	v_add_f32_e32 v235, v205, v204
	v_add_f32_e32 v243, v206, v207
	v_add_f32_e32 v235, v235, v243
	v_add_f32_e32 v236, v209, v208
	v_add_f32_e32 v244, v210, v211
	v_add_f32_e32 v236, v236, v244
	v_add_f32_e32 v237, v213, v212
	v_add_f32_e32 v245, v214, v215
	v_add_f32_e32 v237, v237, v245
	v_add_f32_e32 v238, v217, v216
	v_add_f32_e32 v246, v218, v219
	v_add_f32_e32 v238, v238, v246
	v_add_f32_e32 v239, v221, v220
	v_add_f32_e32 v247, v222, v223
	v_add_f32_e32 v239, v239, v247
	v_add_f32_e32 v240, v225, v224
	v_add_f32_e32 v248, v226, v227
	v_add_f32_e32 v240, v240, v248
	v_add_f32_e32 v241, v229, v228
	v_add_f32_e32 v249, v230, v231
	v_add_f32_e32 v241, v241, v249
	ds_bpermute_b32 v242, v151, v234
	ds_bpermute_b32 v243, v151, v235
	ds_bpermute_b32 v244, v151, v236
	ds_bpermute_b32 v245, v151, v237
	ds_bpermute_b32 v246, v151, v238
	ds_bpermute_b32 v247, v151, v239
	ds_bpermute_b32 v248, v151, v240
	ds_bpermute_b32 v249, v151, v241
	s_waitcnt lgkmcnt(0)
	v_add_f32_e32 v234, v234, v242
	v_add_f32_e32 v235, v235, v243
	v_add_f32_e32 v236, v236, v244
	v_add_f32_e32 v237, v237, v245
	v_add_f32_e32 v238, v238, v246
	v_add_f32_e32 v239, v239, v247
	v_add_f32_e32 v240, v240, v248
	v_add_f32_e32 v241, v241, v249
	ds_bpermute_b32 v242, v152, v234
	ds_bpermute_b32 v243, v152, v235
	ds_bpermute_b32 v244, v152, v236
	ds_bpermute_b32 v245, v152, v237
	ds_bpermute_b32 v246, v152, v238
	ds_bpermute_b32 v247, v152, v239
	ds_bpermute_b32 v248, v152, v240
	ds_bpermute_b32 v249, v152, v241
	s_waitcnt lgkmcnt(0)
	v_add_f32_e32 v234, v234, v242
	v_add_f32_e32 v235, v235, v243
	v_add_f32_e32 v236, v236, v244
	v_add_f32_e32 v237, v237, v245
	v_add_f32_e32 v238, v238, v246
	v_add_f32_e32 v239, v239, v247
	v_add_f32_e32 v240, v240, v248
	v_add_f32_e32 v241, v241, v249
	v_fmamk_f32 v234, v234, 0x3a800000, v171
	v_cmp_gt_f32_e32 vcc, s9, v234
	v_mul_f32_e32 v242, 0x4b800000, v234
	s_nop 0
	v_cndmask_b32_e32 v234, v234, v242, vcc
	v_rsq_f32_e32 v234, v234
	s_nop 0
	v_mul_f32_e32 v242, 0x45800000, v234
	v_cndmask_b32_e32 v200, v234, v242, vcc
	v_fmamk_f32 v235, v235, 0x3a800000, v171
	v_cmp_gt_f32_e32 vcc, s9, v235
	v_mul_f32_e32 v243, 0x4b800000, v235
	s_nop 0
	v_cndmask_b32_e32 v235, v235, v243, vcc
	v_rsq_f32_e32 v235, v235
	s_nop 0
	v_mul_f32_e32 v243, 0x45800000, v235
	v_cndmask_b32_e32 v202, v235, v243, vcc
	v_fmamk_f32 v236, v236, 0x3a800000, v171
	v_cmp_gt_f32_e32 vcc, s9, v236
	v_mul_f32_e32 v244, 0x4b800000, v236
	s_nop 0
	v_cndmask_b32_e32 v236, v236, v244, vcc
	v_rsq_f32_e32 v236, v236
	s_nop 0
	v_mul_f32_e32 v244, 0x45800000, v236
	v_cndmask_b32_e32 v204, v236, v244, vcc
	v_fmamk_f32 v237, v237, 0x3a800000, v171
	v_cmp_gt_f32_e32 vcc, s9, v237
	v_mul_f32_e32 v245, 0x4b800000, v237
	s_nop 0
	v_cndmask_b32_e32 v237, v237, v245, vcc
	v_rsq_f32_e32 v237, v237
	s_nop 0
	v_mul_f32_e32 v245, 0x45800000, v237
	v_cndmask_b32_e32 v206, v237, v245, vcc
	v_fmamk_f32 v238, v238, 0x3a800000, v171
	v_cmp_gt_f32_e32 vcc, s9, v238
	v_mul_f32_e32 v246, 0x4b800000, v238
	s_nop 0
	v_cndmask_b32_e32 v238, v238, v246, vcc
	v_rsq_f32_e32 v238, v238
	s_nop 0
	v_mul_f32_e32 v246, 0x45800000, v238
	v_cndmask_b32_e32 v208, v238, v246, vcc
	v_fmamk_f32 v239, v239, 0x3a800000, v171
	v_cmp_gt_f32_e32 vcc, s9, v239
; __device__ __forceinline__ unsigned pk2(float lo, float hi) { return pg8::cvt_pk_bf16(lo, hi); }
; __device__ __forceinline__ float siluf(float x) { return x * sigm(x); }
;     __device__ __forceinline__ void operator()(const pg8::f32x4 (&acc)[2][2][4][2], const pg8::Unit& u, int wr, int wc, int fr, int fq) const {
;     ...
;                 const size_t row = (size_t)(row0 + ai * 128 + m * 16);
;                 const float rs = row_rs4(ssq, row, fq);
;                 const pg8::f32x4 g0 = acc[ai][0][m][0] * rs, g1 = acc[ai][0][m][1] * rs, u0 = acc[ai][1][m][0] * rs, u1 = acc[ai][1][m][1] * rs;
;                 u32x4 w;
;                 w.x = pk2(siluf(g0[0]) * u0[0], siluf(g0[1]) * u0[1]); w.y = pk2(siluf(g0[2]) * u0[2], siluf(g0[3]) * u0[3]);
;                 w.z = pk2(siluf(g1[0]) * u1[0], siluf(g1[1]) * u1[1]); w.w = pk2(siluf(g1[2]) * u1[2], siluf(g1[3]) * u1[3]);
;                 *(u32x4*)(H + row * DFF + col0) = w;
	v_mul_f32_e32 v247, 0x4b800000, v239
	s_nop 0
	v_cndmask_b32_e32 v239, v239, v247, vcc
	v_rsq_f32_e32 v239, v239
	s_nop 0
	v_mul_f32_e32 v247, 0x45800000, v239
	v_cndmask_b32_e32 v210, v239, v247, vcc
	v_fmamk_f32 v240, v240, 0x3a800000, v171
	v_cmp_gt_f32_e32 vcc, s9, v240
	v_mul_f32_e32 v248, 0x4b800000, v240
	s_nop 0
	v_cndmask_b32_e32 v240, v240, v248, vcc
	v_rsq_f32_e32 v240, v240
	s_nop 0
	v_mul_f32_e32 v248, 0x45800000, v240
	v_cndmask_b32_e32 v212, v240, v248, vcc
	v_fmamk_f32 v241, v241, 0x3a800000, v171
	v_cmp_gt_f32_e32 vcc, s9, v241
	v_mul_f32_e32 v249, 0x4b800000, v241
	s_nop 0
	v_cndmask_b32_e32 v241, v241, v249, vcc
	v_rsq_f32_e32 v241, v241
	s_nop 0
	v_mul_f32_e32 v249, 0x45800000, v241
	v_cndmask_b32_e32 v214, v241, v249, vcc
	v_pk_mul_f32 v[124:125], v[124:125], v[200:201] op_sel_hi:[1,0]
	v_pk_mul_f32 v[126:127], v[126:127], v[200:201] op_sel_hi:[1,0]
	v_pk_mul_f32 v[120:121], v[120:121], v[200:201] op_sel_hi:[1,0]
	v_pk_mul_f32 v[122:123], v[122:123], v[200:201] op_sel_hi:[1,0]
	v_pk_mul_f32 v[116:117], v[116:117], v[200:201] op_sel_hi:[1,0]
	v_pk_mul_f32 v[118:119], v[118:119], v[200:201] op_sel_hi:[1,0]
	v_pk_mul_f32 v[112:113], v[112:113], v[200:201] op_sel_hi:[1,0]
	v_pk_mul_f32 v[114:115], v[114:115], v[200:201] op_sel_hi:[1,0]
	v_mul_f32_e32 v216, 0xbfb8aa3b, v124
	v_mul_f32_e32 v217, 0xbfb8aa3b, v125
	v_mul_f32_e32 v218, 0xbfb8aa3b, v126
	v_mul_f32_e32 v219, 0xbfb8aa3b, v127
	v_exp_f32_e32 v216, v216
	v_exp_f32_e32 v217, v217
	v_exp_f32_e32 v218, v218
	v_exp_f32_e32 v219, v219
	v_add_f32_e32 v216, 1.0, v216
	v_add_f32_e32 v217, 1.0, v217
	v_add_f32_e32 v218, 1.0, v218
	v_add_f32_e32 v219, 1.0, v219
	v_rcp_f32_e32 v216, v216
	v_rcp_f32_e32 v217, v217
	v_rcp_f32_e32 v218, v218
	v_rcp_f32_e32 v219, v219
	v_mul_f32_e32 v216, v124, v216
	v_mul_f32_e32 v217, v125, v217
	v_mul_f32_e32 v218, v126, v218
	v_mul_f32_e32 v219, v127, v219
	v_mul_f32_e32 v216, v116, v216
	v_mul_f32_e32 v217, v117, v217
	v_mul_f32_e32 v218, v118, v218
	v_mul_f32_e32 v219, v119, v219
	v_cvt_pk_bf16_f32 v220, v216, v217
	v_cvt_pk_bf16_f32 v221, v218, v219
	v_mul_f32_e32 v216, 0xbfb8aa3b, v120
	v_mul_f32_e32 v217, 0xbfb8aa3b, v121
	v_mul_f32_e32 v218, 0xbfb8aa3b, v122
	v_mul_f32_e32 v219, 0xbfb8aa3b, v123
	v_exp_f32_e32 v216, v216
	v_exp_f32_e32 v217, v217
	v_exp_f32_e32 v218, v218
	v_exp_f32_e32 v219, v219
	v_add_f32_e32 v216, 1.0, v216
	v_add_f32_e32 v217, 1.0, v217
	v_add_f32_e32 v218, 1.0, v218
	v_add_f32_e32 v219, 1.0, v219
	v_rcp_f32_e32 v216, v216
	v_rcp_f32_e32 v217, v217
	v_rcp_f32_e32 v218, v218
	v_rcp_f32_e32 v219, v219
	v_mul_f32_e32 v216, v120, v216
	v_mul_f32_e32 v217, v121, v217
	v_mul_f32_e32 v218, v122, v218
	v_mul_f32_e32 v219, v123, v219
	v_mul_f32_e32 v216, v112, v216
	v_mul_f32_e32 v217, v113, v217
	v_mul_f32_e32 v218, v114, v218
	v_mul_f32_e32 v219, v115, v219
	v_cvt_pk_bf16_f32 v222, v216, v217
	v_cvt_pk_bf16_f32 v223, v218, v219
	v_mov_b32_e32 v232, v144
	v_mad_i64_i32 v[232:233], s[0:1], v232, s11, v[156:157]
	v_lshl_add_u64 v[232:233], v[232:233], 0, v[154:155]
	global_store_dwordx4 v[232:233], v[220:223], off
	v_pk_mul_f32 v[108:109], v[108:109], v[202:203] op_sel_hi:[1,0]
	v_pk_mul_f32 v[110:111], v[110:111], v[202:203] op_sel_hi:[1,0]
	v_pk_mul_f32 v[104:105], v[104:105], v[202:203] op_sel_hi:[1,0]
	v_pk_mul_f32 v[106:107], v[106:107], v[202:203] op_sel_hi:[1,0]
	v_pk_mul_f32 v[100:101], v[100:101], v[202:203] op_sel_hi:[1,0]
	v_pk_mul_f32 v[102:103], v[102:103], v[202:203] op_sel_hi:[1,0]
	v_pk_mul_f32 v[96:97], v[96:97], v[202:203] op_sel_hi:[1,0]
	v_pk_mul_f32 v[98:99], v[98:99], v[202:203] op_sel_hi:[1,0]
	v_mul_f32_e32 v216, 0xbfb8aa3b, v108
	v_mul_f32_e32 v217, 0xbfb8aa3b, v109
	v_mul_f32_e32 v218, 0xbfb8aa3b, v110
	v_mul_f32_e32 v219, 0xbfb8aa3b, v111
	v_exp_f32_e32 v216, v216
	v_exp_f32_e32 v217, v217
	v_exp_f32_e32 v218, v218
	v_exp_f32_e32 v219, v219
	v_add_f32_e32 v216, 1.0, v216
	v_add_f32_e32 v217, 1.0, v217
	v_add_f32_e32 v218, 1.0, v218
	v_add_f32_e32 v219, 1.0, v219
	v_rcp_f32_e32 v216, v216
	v_rcp_f32_e32 v217, v217
	v_rcp_f32_e32 v218, v218
	v_rcp_f32_e32 v219, v219
	v_mul_f32_e32 v216, v108, v216
	v_mul_f32_e32 v217, v109, v217
	v_mul_f32_e32 v218, v110, v218
	v_mul_f32_e32 v219, v111, v219
	v_mul_f32_e32 v216, v100, v216
	v_mul_f32_e32 v217, v101, v217
	v_mul_f32_e32 v218, v102, v218
	v_mul_f32_e32 v219, v103, v219
	v_cvt_pk_bf16_f32 v224, v216, v217
	v_cvt_pk_bf16_f32 v225, v218, v219
	v_mul_f32_e32 v216, 0xbfb8aa3b, v104
	v_mul_f32_e32 v217, 0xbfb8aa3b, v105
	v_mul_f32_e32 v218, 0xbfb8aa3b, v106
	v_mul_f32_e32 v219, 0xbfb8aa3b, v107
	v_exp_f32_e32 v216, v216
	v_exp_f32_e32 v217, v217
	v_exp_f32_e32 v218, v218
	v_exp_f32_e32 v219, v219
	v_add_f32_e32 v216, 1.0, v216
	v_add_f32_e32 v217, 1.0, v217
	v_add_f32_e32 v218, 1.0, v218
	v_add_f32_e32 v219, 1.0, v219
	v_rcp_f32_e32 v216, v216
	v_rcp_f32_e32 v217, v217
	v_rcp_f32_e32 v218, v218
	v_rcp_f32_e32 v219, v219
	v_mul_f32_e32 v216, v104, v216
	v_mul_f32_e32 v217, v105, v217
	v_mul_f32_e32 v218, v106, v218
	v_mul_f32_e32 v219, v107, v219
	v_mul_f32_e32 v216, v96, v216
	v_mul_f32_e32 v217, v97, v217
	v_mul_f32_e32 v218, v98, v218
	v_mul_f32_e32 v219, v99, v219
	v_cvt_pk_bf16_f32 v226, v216, v217
	v_cvt_pk_bf16_f32 v227, v218, v219
	v_add_u32_e32 v232, 0x10, v144
	v_mad_i64_i32 v[232:233], s[0:1], v232, s11, v[156:157]
	v_lshl_add_u64 v[232:233], v[232:233], 0, v[154:155]
	global_store_dwordx4 v[232:233], v[224:227], off
	v_pk_mul_f32 v[92:93], v[92:93], v[204:205] op_sel_hi:[1,0]
	v_pk_mul_f32 v[94:95], v[94:95], v[204:205] op_sel_hi:[1,0]
	v_pk_mul_f32 v[88:89], v[88:89], v[204:205] op_sel_hi:[1,0]
	v_pk_mul_f32 v[90:91], v[90:91], v[204:205] op_sel_hi:[1,0]
; __device__ __forceinline__ unsigned pk2(float lo, float hi) { return pg8::cvt_pk_bf16(lo, hi); }
; __device__ __forceinline__ float siluf(float x) { return x * sigm(x); }
;     __device__ __forceinline__ void operator()(const pg8::f32x4 (&acc)[2][2][4][2], const pg8::Unit& u, int wr, int wc, int fr, int fq) const {
;     ...
;                 const size_t row = (size_t)(row0 + ai * 128 + m * 16);
;                 const float rs = row_rs4(ssq, row, fq);
;                 const pg8::f32x4 g0 = acc[ai][0][m][0] * rs, g1 = acc[ai][0][m][1] * rs, u0 = acc[ai][1][m][0] * rs, u1 = acc[ai][1][m][1] * rs;
;                 u32x4 w;
;                 w.x = pk2(siluf(g0[0]) * u0[0], siluf(g0[1]) * u0[1]); w.y = pk2(siluf(g0[2]) * u0[2], siluf(g0[3]) * u0[3]);
;                 w.z = pk2(siluf(g1[0]) * u1[0], siluf(g1[1]) * u1[1]); w.w = pk2(siluf(g1[2]) * u1[2], siluf(g1[3]) * u1[3]);
;                 *(u32x4*)(H + row * DFF + col0) = w;
	v_pk_mul_f32 v[84:85], v[84:85], v[204:205] op_sel_hi:[1,0]
	v_pk_mul_f32 v[86:87], v[86:87], v[204:205] op_sel_hi:[1,0]
	v_pk_mul_f32 v[80:81], v[80:81], v[204:205] op_sel_hi:[1,0]
	v_pk_mul_f32 v[82:83], v[82:83], v[204:205] op_sel_hi:[1,0]
	v_mul_f32_e32 v216, 0xbfb8aa3b, v92
	v_mul_f32_e32 v217, 0xbfb8aa3b, v93
	v_mul_f32_e32 v218, 0xbfb8aa3b, v94
	v_mul_f32_e32 v219, 0xbfb8aa3b, v95
	v_exp_f32_e32 v216, v216
	v_exp_f32_e32 v217, v217
	v_exp_f32_e32 v218, v218
	v_exp_f32_e32 v219, v219
	v_add_f32_e32 v216, 1.0, v216
	v_add_f32_e32 v217, 1.0, v217
	v_add_f32_e32 v218, 1.0, v218
	v_add_f32_e32 v219, 1.0, v219
	v_rcp_f32_e32 v216, v216
	v_rcp_f32_e32 v217, v217
	v_rcp_f32_e32 v218, v218
	v_rcp_f32_e32 v219, v219
	v_mul_f32_e32 v216, v92, v216
	v_mul_f32_e32 v217, v93, v217
	v_mul_f32_e32 v218, v94, v218
	v_mul_f32_e32 v219, v95, v219
	v_mul_f32_e32 v216, v84, v216
	v_mul_f32_e32 v217, v85, v217
	v_mul_f32_e32 v218, v86, v218
	v_mul_f32_e32 v219, v87, v219
	v_cvt_pk_bf16_f32 v220, v216, v217
	v_cvt_pk_bf16_f32 v221, v218, v219
	v_mul_f32_e32 v216, 0xbfb8aa3b, v88
	v_mul_f32_e32 v217, 0xbfb8aa3b, v89
	v_mul_f32_e32 v218, 0xbfb8aa3b, v90
	v_mul_f32_e32 v219, 0xbfb8aa3b, v91
	v_exp_f32_e32 v216, v216
	v_exp_f32_e32 v217, v217
	v_exp_f32_e32 v218, v218
	v_exp_f32_e32 v219, v219
	v_add_f32_e32 v216, 1.0, v216
	v_add_f32_e32 v217, 1.0, v217
	v_add_f32_e32 v218, 1.0, v218
	v_add_f32_e32 v219, 1.0, v219
	v_rcp_f32_e32 v216, v216
	v_rcp_f32_e32 v217, v217
	v_rcp_f32_e32 v218, v218
	v_rcp_f32_e32 v219, v219
	v_mul_f32_e32 v216, v88, v216
	v_mul_f32_e32 v217, v89, v217
	v_mul_f32_e32 v218, v90, v218
	v_mul_f32_e32 v219, v91, v219
	v_mul_f32_e32 v216, v80, v216
	v_mul_f32_e32 v217, v81, v217
	v_mul_f32_e32 v218, v82, v218
	v_mul_f32_e32 v219, v83, v219
	v_cvt_pk_bf16_f32 v222, v216, v217
	v_cvt_pk_bf16_f32 v223, v218, v219
	v_add_u32_e32 v232, 0x20, v144
	v_mad_i64_i32 v[232:233], s[0:1], v232, s11, v[156:157]
	v_lshl_add_u64 v[232:233], v[232:233], 0, v[154:155]
	global_store_dwordx4 v[232:233], v[220:223], off
	v_pk_mul_f32 v[76:77], v[76:77], v[206:207] op_sel_hi:[1,0]
	v_pk_mul_f32 v[78:79], v[78:79], v[206:207] op_sel_hi:[1,0]
	v_pk_mul_f32 v[72:73], v[72:73], v[206:207] op_sel_hi:[1,0]
	v_pk_mul_f32 v[74:75], v[74:75], v[206:207] op_sel_hi:[1,0]
	v_pk_mul_f32 v[68:69], v[68:69], v[206:207] op_sel_hi:[1,0]
	v_pk_mul_f32 v[70:71], v[70:71], v[206:207] op_sel_hi:[1,0]
	v_pk_mul_f32 v[64:65], v[64:65], v[206:207] op_sel_hi:[1,0]
	v_pk_mul_f32 v[66:67], v[66:67], v[206:207] op_sel_hi:[1,0]
	v_mul_f32_e32 v216, 0xbfb8aa3b, v76
	v_mul_f32_e32 v217, 0xbfb8aa3b, v77
	v_mul_f32_e32 v218, 0xbfb8aa3b, v78
	v_mul_f32_e32 v219, 0xbfb8aa3b, v79
	v_exp_f32_e32 v216, v216
	v_exp_f32_e32 v217, v217
	v_exp_f32_e32 v218, v218
	v_exp_f32_e32 v219, v219
	v_add_f32_e32 v216, 1.0, v216
	v_add_f32_e32 v217, 1.0, v217
	v_add_f32_e32 v218, 1.0, v218
	v_add_f32_e32 v219, 1.0, v219
	v_rcp_f32_e32 v216, v216
	v_rcp_f32_e32 v217, v217
	v_rcp_f32_e32 v218, v218
	v_rcp_f32_e32 v219, v219
	v_mul_f32_e32 v216, v76, v216
	v_mul_f32_e32 v217, v77, v217
	v_mul_f32_e32 v218, v78, v218
	v_mul_f32_e32 v219, v79, v219
	v_mul_f32_e32 v216, v68, v216
	v_mul_f32_e32 v217, v69, v217
	v_mul_f32_e32 v218, v70, v218
	v_mul_f32_e32 v219, v71, v219
	v_cvt_pk_bf16_f32 v224, v216, v217
	v_cvt_pk_bf16_f32 v225, v218, v219
	v_mul_f32_e32 v216, 0xbfb8aa3b, v72
	v_mul_f32_e32 v217, 0xbfb8aa3b, v73
	v_mul_f32_e32 v218, 0xbfb8aa3b, v74
	v_mul_f32_e32 v219, 0xbfb8aa3b, v75
	v_exp_f32_e32 v216, v216
	v_exp_f32_e32 v217, v217
	v_exp_f32_e32 v218, v218
	v_exp_f32_e32 v219, v219
	v_add_f32_e32 v216, 1.0, v216
	v_add_f32_e32 v217, 1.0, v217
	v_add_f32_e32 v218, 1.0, v218
	v_add_f32_e32 v219, 1.0, v219
	v_rcp_f32_e32 v216, v216
	v_rcp_f32_e32 v217, v217
	v_rcp_f32_e32 v218, v218
	v_rcp_f32_e32 v219, v219
	v_mul_f32_e32 v216, v72, v216
	v_mul_f32_e32 v217, v73, v217
	v_mul_f32_e32 v218, v74, v218
	v_mul_f32_e32 v219, v75, v219
	v_mul_f32_e32 v216, v64, v216
	v_mul_f32_e32 v217, v65, v217
	v_mul_f32_e32 v218, v66, v218
	v_mul_f32_e32 v219, v67, v219
	v_cvt_pk_bf16_f32 v226, v216, v217
	v_cvt_pk_bf16_f32 v227, v218, v219
	v_add_u32_e32 v232, 0x30, v144
	v_mad_i64_i32 v[232:233], s[0:1], v232, s11, v[156:157]
	v_lshl_add_u64 v[232:233], v[232:233], 0, v[154:155]
	global_store_dwordx4 v[232:233], v[224:227], off
	v_pk_mul_f32 v[60:61], v[60:61], v[208:209] op_sel_hi:[1,0]
	v_pk_mul_f32 v[62:63], v[62:63], v[208:209] op_sel_hi:[1,0]
	v_pk_mul_f32 v[56:57], v[56:57], v[208:209] op_sel_hi:[1,0]
	v_pk_mul_f32 v[58:59], v[58:59], v[208:209] op_sel_hi:[1,0]
	v_pk_mul_f32 v[52:53], v[52:53], v[208:209] op_sel_hi:[1,0]
	v_pk_mul_f32 v[54:55], v[54:55], v[208:209] op_sel_hi:[1,0]
	v_pk_mul_f32 v[48:49], v[48:49], v[208:209] op_sel_hi:[1,0]
	v_pk_mul_f32 v[50:51], v[50:51], v[208:209] op_sel_hi:[1,0]
	v_mul_f32_e32 v216, 0xbfb8aa3b, v60
	v_mul_f32_e32 v217, 0xbfb8aa3b, v61
	v_mul_f32_e32 v218, 0xbfb8aa3b, v62
	v_mul_f32_e32 v219, 0xbfb8aa3b, v63
	v_exp_f32_e32 v216, v216
	v_exp_f32_e32 v217, v217
	v_exp_f32_e32 v218, v218
	v_exp_f32_e32 v219, v219
	v_add_f32_e32 v216, 1.0, v216
	v_add_f32_e32 v217, 1.0, v217
	v_add_f32_e32 v218, 1.0, v218
	v_add_f32_e32 v219, 1.0, v219
	v_rcp_f32_e32 v216, v216
	v_rcp_f32_e32 v217, v217
	v_rcp_f32_e32 v218, v218
	v_rcp_f32_e32 v219, v219
	v_mul_f32_e32 v216, v60, v216
	v_mul_f32_e32 v217, v61, v217
	v_mul_f32_e32 v218, v62, v218
	v_mul_f32_e32 v219, v63, v219
	v_mul_f32_e32 v216, v52, v216
	v_mul_f32_e32 v217, v53, v217
	v_mul_f32_e32 v218, v54, v218
	v_mul_f32_e32 v219, v55, v219
	v_cvt_pk_bf16_f32 v220, v216, v217
	v_cvt_pk_bf16_f32 v221, v218, v219
	v_mul_f32_e32 v216, 0xbfb8aa3b, v56
; __device__ __forceinline__ unsigned pk2(float lo, float hi) { return pg8::cvt_pk_bf16(lo, hi); }
; __device__ __forceinline__ float siluf(float x) { return x * sigm(x); }
;     __device__ __forceinline__ void operator()(const pg8::f32x4 (&acc)[2][2][4][2], const pg8::Unit& u, int wr, int wc, int fr, int fq) const {
;     ...
;                 const size_t row = (size_t)(row0 + ai * 128 + m * 16);
;                 const float rs = row_rs4(ssq, row, fq);
;                 const pg8::f32x4 g0 = acc[ai][0][m][0] * rs, g1 = acc[ai][0][m][1] * rs, u0 = acc[ai][1][m][0] * rs, u1 = acc[ai][1][m][1] * rs;
;                 u32x4 w;
;                 w.x = pk2(siluf(g0[0]) * u0[0], siluf(g0[1]) * u0[1]); w.y = pk2(siluf(g0[2]) * u0[2], siluf(g0[3]) * u0[3]);
;                 w.z = pk2(siluf(g1[0]) * u1[0], siluf(g1[1]) * u1[1]); w.w = pk2(siluf(g1[2]) * u1[2], siluf(g1[3]) * u1[3]);
;                 *(u32x4*)(H + row * DFF + col0) = w;
	v_mul_f32_e32 v217, 0xbfb8aa3b, v57
	v_mul_f32_e32 v218, 0xbfb8aa3b, v58
	v_mul_f32_e32 v219, 0xbfb8aa3b, v59
	v_exp_f32_e32 v216, v216
	v_exp_f32_e32 v217, v217
	v_exp_f32_e32 v218, v218
	v_exp_f32_e32 v219, v219
	v_add_f32_e32 v216, 1.0, v216
	v_add_f32_e32 v217, 1.0, v217
	v_add_f32_e32 v218, 1.0, v218
	v_add_f32_e32 v219, 1.0, v219
	v_rcp_f32_e32 v216, v216
	v_rcp_f32_e32 v217, v217
	v_rcp_f32_e32 v218, v218
	v_rcp_f32_e32 v219, v219
	v_mul_f32_e32 v216, v56, v216
	v_mul_f32_e32 v217, v57, v217
	v_mul_f32_e32 v218, v58, v218
	v_mul_f32_e32 v219, v59, v219
	v_mul_f32_e32 v216, v48, v216
	v_mul_f32_e32 v217, v49, v217
	v_mul_f32_e32 v218, v50, v218
	v_mul_f32_e32 v219, v51, v219
	v_cvt_pk_bf16_f32 v222, v216, v217
	v_cvt_pk_bf16_f32 v223, v218, v219
	v_add_u32_e32 v232, 0x80, v144
	v_mad_i64_i32 v[232:233], s[0:1], v232, s11, v[156:157]
	v_lshl_add_u64 v[232:233], v[232:233], 0, v[154:155]
	global_store_dwordx4 v[232:233], v[220:223], off
	v_pk_mul_f32 v[44:45], v[44:45], v[210:211] op_sel_hi:[1,0]
	v_pk_mul_f32 v[46:47], v[46:47], v[210:211] op_sel_hi:[1,0]
	v_pk_mul_f32 v[40:41], v[40:41], v[210:211] op_sel_hi:[1,0]
	v_pk_mul_f32 v[42:43], v[42:43], v[210:211] op_sel_hi:[1,0]
	v_pk_mul_f32 v[36:37], v[36:37], v[210:211] op_sel_hi:[1,0]
	v_pk_mul_f32 v[38:39], v[38:39], v[210:211] op_sel_hi:[1,0]
	v_pk_mul_f32 v[32:33], v[32:33], v[210:211] op_sel_hi:[1,0]
	v_pk_mul_f32 v[34:35], v[34:35], v[210:211] op_sel_hi:[1,0]
	v_mul_f32_e32 v216, 0xbfb8aa3b, v44
	v_mul_f32_e32 v217, 0xbfb8aa3b, v45
	v_mul_f32_e32 v218, 0xbfb8aa3b, v46
	v_mul_f32_e32 v219, 0xbfb8aa3b, v47
	v_exp_f32_e32 v216, v216
	v_exp_f32_e32 v217, v217
	v_exp_f32_e32 v218, v218
	v_exp_f32_e32 v219, v219
	v_add_f32_e32 v216, 1.0, v216
	v_add_f32_e32 v217, 1.0, v217
	v_add_f32_e32 v218, 1.0, v218
	v_add_f32_e32 v219, 1.0, v219
	v_rcp_f32_e32 v216, v216
	v_rcp_f32_e32 v217, v217
	v_rcp_f32_e32 v218, v218
	v_rcp_f32_e32 v219, v219
	v_mul_f32_e32 v216, v44, v216
	v_mul_f32_e32 v217, v45, v217
	v_mul_f32_e32 v218, v46, v218
	v_mul_f32_e32 v219, v47, v219
	v_mul_f32_e32 v216, v36, v216
	v_mul_f32_e32 v217, v37, v217
	v_mul_f32_e32 v218, v38, v218
	v_mul_f32_e32 v219, v39, v219
	v_cvt_pk_bf16_f32 v224, v216, v217
	v_cvt_pk_bf16_f32 v225, v218, v219
	v_mul_f32_e32 v216, 0xbfb8aa3b, v40
	v_mul_f32_e32 v217, 0xbfb8aa3b, v41
	v_mul_f32_e32 v218, 0xbfb8aa3b, v42
	v_mul_f32_e32 v219, 0xbfb8aa3b, v43
	v_exp_f32_e32 v216, v216
	v_exp_f32_e32 v217, v217
	v_exp_f32_e32 v218, v218
	v_exp_f32_e32 v219, v219
	v_add_f32_e32 v216, 1.0, v216
	v_add_f32_e32 v217, 1.0, v217
	v_add_f32_e32 v218, 1.0, v218
	v_add_f32_e32 v219, 1.0, v219
	v_rcp_f32_e32 v216, v216
	v_rcp_f32_e32 v217, v217
	v_rcp_f32_e32 v218, v218
	v_rcp_f32_e32 v219, v219
	v_mul_f32_e32 v216, v40, v216
	v_mul_f32_e32 v217, v41, v217
	v_mul_f32_e32 v218, v42, v218
	v_mul_f32_e32 v219, v43, v219
	v_mul_f32_e32 v216, v32, v216
	v_mul_f32_e32 v217, v33, v217
	v_mul_f32_e32 v218, v34, v218
	v_mul_f32_e32 v219, v35, v219
	v_cvt_pk_bf16_f32 v226, v216, v217
	v_cvt_pk_bf16_f32 v227, v218, v219
	v_add_u32_e32 v232, 0x90, v144
	v_mad_i64_i32 v[232:233], s[0:1], v232, s11, v[156:157]
	v_lshl_add_u64 v[232:233], v[232:233], 0, v[154:155]
	global_store_dwordx4 v[232:233], v[224:227], off
	v_pk_mul_f32 v[28:29], v[28:29], v[212:213] op_sel_hi:[1,0]
	v_pk_mul_f32 v[30:31], v[30:31], v[212:213] op_sel_hi:[1,0]
	v_pk_mul_f32 v[24:25], v[24:25], v[212:213] op_sel_hi:[1,0]
	v_pk_mul_f32 v[26:27], v[26:27], v[212:213] op_sel_hi:[1,0]
	v_pk_mul_f32 v[20:21], v[20:21], v[212:213] op_sel_hi:[1,0]
	v_pk_mul_f32 v[22:23], v[22:23], v[212:213] op_sel_hi:[1,0]
	v_pk_mul_f32 v[16:17], v[16:17], v[212:213] op_sel_hi:[1,0]
	v_pk_mul_f32 v[18:19], v[18:19], v[212:213] op_sel_hi:[1,0]
	v_mul_f32_e32 v216, 0xbfb8aa3b, v28
	v_mul_f32_e32 v217, 0xbfb8aa3b, v29
	v_mul_f32_e32 v218, 0xbfb8aa3b, v30
	v_mul_f32_e32 v219, 0xbfb8aa3b, v31
	v_exp_f32_e32 v216, v216
	v_exp_f32_e32 v217, v217
	v_exp_f32_e32 v218, v218
	v_exp_f32_e32 v219, v219
; __device__ __forceinline__ unsigned pk2(float lo, float hi) { return pg8::cvt_pk_bf16(lo, hi); }
; __device__ __forceinline__ float siluf(float x) { return x * sigm(x); }
;     __device__ __forceinline__ void operator()(const pg8::f32x4 (&acc)[2][2][4][2], const pg8::Unit& u, int wr, int wc, int fr, int fq) const {
;     ...
;                 const size_t row = (size_t)(row0 + ai * 128 + m * 16);
;                 const float rs = row_rs4(ssq, row, fq);
;                 const pg8::f32x4 g0 = acc[ai][0][m][0] * rs, g1 = acc[ai][0][m][1] * rs, u0 = acc[ai][1][m][0] * rs, u1 = acc[ai][1][m][1] * rs;
;                 u32x4 w;
;                 w.x = pk2(siluf(g0[0]) * u0[0], siluf(g0[1]) * u0[1]); w.y = pk2(siluf(g0[2]) * u0[2], siluf(g0[3]) * u0[3]);
;                 w.z = pk2(siluf(g1[0]) * u1[0], siluf(g1[1]) * u1[1]); w.w = pk2(siluf(g1[2]) * u1[2], siluf(g1[3]) * u1[3]);
;                 *(u32x4*)(H + row * DFF + col0) = w;
	v_add_f32_e32 v216, 1.0, v216
	v_add_f32_e32 v217, 1.0, v217
	v_add_f32_e32 v218, 1.0, v218
	v_add_f32_e32 v219, 1.0, v219
	v_rcp_f32_e32 v216, v216
	v_rcp_f32_e32 v217, v217
	v_rcp_f32_e32 v218, v218
	v_rcp_f32_e32 v219, v219
	v_mul_f32_e32 v216, v28, v216
	v_mul_f32_e32 v217, v29, v217
	v_mul_f32_e32 v218, v30, v218
	v_mul_f32_e32 v219, v31, v219
	v_mul_f32_e32 v216, v20, v216
	v_mul_f32_e32 v217, v21, v217
	v_mul_f32_e32 v218, v22, v218
	v_mul_f32_e32 v219, v23, v219
	v_cvt_pk_bf16_f32 v220, v216, v217
	v_cvt_pk_bf16_f32 v221, v218, v219
	v_mul_f32_e32 v216, 0xbfb8aa3b, v24
	v_mul_f32_e32 v217, 0xbfb8aa3b, v25
	v_mul_f32_e32 v218, 0xbfb8aa3b, v26
	v_mul_f32_e32 v219, 0xbfb8aa3b, v27
	v_exp_f32_e32 v216, v216
	v_exp_f32_e32 v217, v217
	v_exp_f32_e32 v218, v218
	v_exp_f32_e32 v219, v219
	v_add_f32_e32 v216, 1.0, v216
	v_add_f32_e32 v217, 1.0, v217
	v_add_f32_e32 v218, 1.0, v218
	v_add_f32_e32 v219, 1.0, v219
	v_rcp_f32_e32 v216, v216
	v_rcp_f32_e32 v217, v217
	v_rcp_f32_e32 v218, v218
	v_rcp_f32_e32 v219, v219
	v_mul_f32_e32 v216, v24, v216
	v_mul_f32_e32 v217, v25, v217
	v_mul_f32_e32 v218, v26, v218
	v_mul_f32_e32 v219, v27, v219
	v_mul_f32_e32 v216, v16, v216
	v_mul_f32_e32 v217, v17, v217
	v_mul_f32_e32 v218, v18, v218
	v_mul_f32_e32 v219, v19, v219
	v_cvt_pk_bf16_f32 v222, v216, v217
	v_cvt_pk_bf16_f32 v223, v218, v219
	v_add_u32_e32 v232, 0xa0, v144
	v_mad_i64_i32 v[232:233], s[0:1], v232, s11, v[156:157]
	v_lshl_add_u64 v[232:233], v[232:233], 0, v[154:155]
	global_store_dwordx4 v[232:233], v[220:223], off
	v_pk_mul_f32 v[12:13], v[12:13], v[214:215] op_sel_hi:[1,0]
	v_pk_mul_f32 v[14:15], v[14:15], v[214:215] op_sel_hi:[1,0]
	v_pk_mul_f32 v[8:9], v[8:9], v[214:215] op_sel_hi:[1,0]
	v_pk_mul_f32 v[10:11], v[10:11], v[214:215] op_sel_hi:[1,0]
	v_pk_mul_f32 v[4:5], v[4:5], v[214:215] op_sel_hi:[1,0]
	v_pk_mul_f32 v[6:7], v[6:7], v[214:215] op_sel_hi:[1,0]
	v_pk_mul_f32 v[0:1], v[0:1], v[214:215] op_sel_hi:[1,0]
	v_pk_mul_f32 v[2:3], v[2:3], v[214:215] op_sel_hi:[1,0]
	v_mul_f32_e32 v216, 0xbfb8aa3b, v12
	v_mul_f32_e32 v217, 0xbfb8aa3b, v13
	v_mul_f32_e32 v218, 0xbfb8aa3b, v14
	v_mul_f32_e32 v219, 0xbfb8aa3b, v15
	v_exp_f32_e32 v216, v216
	v_exp_f32_e32 v217, v217
	v_exp_f32_e32 v218, v218
	v_exp_f32_e32 v219, v219
	v_add_f32_e32 v216, 1.0, v216
	v_add_f32_e32 v217, 1.0, v217
	v_add_f32_e32 v218, 1.0, v218
	v_add_f32_e32 v219, 1.0, v219
	v_rcp_f32_e32 v216, v216
	v_rcp_f32_e32 v217, v217
	v_rcp_f32_e32 v218, v218
	v_rcp_f32_e32 v219, v219
	v_mul_f32_e32 v216, v12, v216
	v_mul_f32_e32 v217, v13, v217
	v_mul_f32_e32 v218, v14, v218
	v_mul_f32_e32 v219, v15, v219
	v_mul_f32_e32 v216, v4, v216
	v_mul_f32_e32 v217, v5, v217
	v_mul_f32_e32 v218, v6, v218
	v_mul_f32_e32 v219, v7, v219
	v_cvt_pk_bf16_f32 v224, v216, v217
	v_cvt_pk_bf16_f32 v225, v218, v219
	v_mul_f32_e32 v216, 0xbfb8aa3b, v8
	v_mul_f32_e32 v217, 0xbfb8aa3b, v9
	v_mul_f32_e32 v218, 0xbfb8aa3b, v10
	v_mul_f32_e32 v219, 0xbfb8aa3b, v11
	v_exp_f32_e32 v216, v216
	v_exp_f32_e32 v217, v217
	v_exp_f32_e32 v218, v218
	v_exp_f32_e32 v219, v219
	v_add_f32_e32 v216, 1.0, v216
	v_add_f32_e32 v217, 1.0, v217
	v_add_f32_e32 v218, 1.0, v218
	v_add_f32_e32 v219, 1.0, v219
	v_rcp_f32_e32 v216, v216
	v_rcp_f32_e32 v217, v217
	v_rcp_f32_e32 v218, v218
	v_rcp_f32_e32 v219, v219
	v_mul_f32_e32 v216, v8, v216
	v_mul_f32_e32 v217, v9, v217
	v_mul_f32_e32 v218, v10, v218
	v_mul_f32_e32 v219, v11, v219
	v_mul_f32_e32 v216, v0, v216
	v_mul_f32_e32 v217, v1, v217
	v_mul_f32_e32 v218, v2, v218
	v_mul_f32_e32 v219, v3, v219
	v_cvt_pk_bf16_f32 v226, v216, v217
	v_cvt_pk_bf16_f32 v227, v218, v219
	v_add_u32_e32 v232, 0xb0, v144
	v_mad_i64_i32 v[232:233], s[0:1], v232, s11, v[156:157]
	v_lshl_add_u64 v[232:233], v[232:233], 0, v[154:155]
	global_store_dwordx4 v[232:233], v[224:227], off
	s_andn2_b64 vcc, exec, s[38:39]
	s_mov_b64 s[0:1], -1
	s_cbranch_vccnz .LBB0_153
	s_andn2_b64 vcc, exec, s[4:5]
	s_cbranch_vccnz .LBB0_152
	s_barrier
	s_branch .LBB0_152
